# attention A: shrink the per-step barrier bubble - V-fragment reads for the next step prefetched before the barrier, staging LDS writes moved into the S-MFMA section (unconditional), global-load addres
# baseline (speedup 1.0000x reference)
; #define FLAS __attribute__((address_space(3)))
; __device__ __forceinline__ void attn_unit_a(FLAS unsigned char* lds, const Unit u) {
;     ...
;     f32x16 pa0, pa1, pb0, pb1; float cbC = 0.f;
;     { bool zi; FA_BIAS(0, pa0, pa1, cbC, zi); if (zi) { pa0 = z16; pa1 = z16; }
;       const FLAS unsigned char* kb = lds + LA_K;
; #pragma unroll
;       for (int d0 = 0; d0 < 4; ++d0) { const int ko = (2 * d0 + hi) * 1024 + ((r32 ^ (2 * d0 + hi)) * 16); const bf16x8 a0 = *(const FLAS bf16x8*)(kb + ko), a1 = *(const FLAS bf16x8*)(kb + ko + 512);
;           pa0 = __builtin_amdgcn_mfma_f32_32x32x16_bf16(a0, qr[d0], pa0, 0, 0, 0); pa1 = __builtin_amdgcn_mfma_f32_32x32x16_bf16(a1, qr[d0], pa1, 0, 0, 0); } }
;     u32x4 pwa[4] = {{0u,0u,0u,0u},{0u,0u,0u,0u},{0u,0u,0u,0u},{0u,0u,0u,0u}}, pwb[4] = {{0u,0u,0u,0u},{0u,0u,0u,0u},{0u,0u,0u,0u},{0u,0u,0u,0u}};
;     ...
;         const int vsp = (i == 0) ? 0 : ((i - 1) & 3);
;         const FLAS unsigned char* vb_ = lds + LA_V + vsp * VBUF + r32 * VPITCH + hi * 16;
;         const FLAS unsigned char* kb = lds + LA_K + ((i + 1) & 1) * KBUF;
;     ...
;         u32x4 vr[3];
; #pragma unroll
;         for (int m = 0; m < 3; ++m) vr[m] = FA_VFRAG(m);
.Lprio_skip:
	s_waitcnt lgkmcnt(0)
	v_readlane_b32 s100, v254, 47
	v_mov_b32_e32 v92, s13
	s_nop 3
	v_mov_b32_e32 v93, s100
	ds_read_b32 v92, v92
	ds_read_b32 v93, v93
	v_sub_f32_e32 v94, v204, v211
	v_add_f32_e32 v96, v128, v94
	v_add_f32_e32 v112, v144, v94
	v_add_f32_e32 v97, v129, v94
	v_add_f32_e32 v113, v145, v94
	v_add_f32_e32 v98, v130, v94
	v_add_f32_e32 v114, v146, v94
	v_add_f32_e32 v99, v131, v94
	v_add_f32_e32 v115, v147, v94
	v_add_f32_e32 v100, v132, v94
	v_add_f32_e32 v116, v148, v94
	v_add_f32_e32 v101, v133, v94
	v_add_f32_e32 v117, v149, v94
	v_add_f32_e32 v102, v134, v94
	v_add_f32_e32 v118, v150, v94
	v_add_f32_e32 v103, v135, v94
	v_add_f32_e32 v119, v151, v94
	v_add_f32_e32 v104, v136, v94
	v_add_f32_e32 v120, v152, v94
	v_add_f32_e32 v105, v137, v94
	v_add_f32_e32 v121, v153, v94
	v_add_f32_e32 v106, v138, v94
	v_add_f32_e32 v122, v154, v94
	v_add_f32_e32 v107, v139, v94
	v_add_f32_e32 v123, v155, v94
	v_add_f32_e32 v108, v140, v94
	v_add_f32_e32 v124, v156, v94
	v_add_f32_e32 v109, v141, v94
	v_add_f32_e32 v125, v157, v94
	v_add_f32_e32 v110, v142, v94
	v_add_f32_e32 v126, v158, v94
	v_add_f32_e32 v111, v143, v94
	v_add_f32_e32 v127, v159, v94
	v_mov_b32_e32 v144, 0x7fc00000
	v_mov_b32_e32 v145, 0x7fc00000
	v_mov_b32_e32 v146, 0x7fc00000
	v_mov_b32_e32 v147, 0x7fc00000
	v_mov_b32_e32 v148, 0x7fc00000
	v_mov_b32_e32 v149, 0x7fc00000
	v_mov_b32_e32 v150, 0x7fc00000
	v_mov_b32_e32 v151, 0x7fc00000
	v_mov_b32_e32 v152, 0x7fc00000
	v_mov_b32_e32 v153, 0x7fc00000
	v_mov_b32_e32 v154, 0x7fc00000
	v_mov_b32_e32 v155, 0x7fc00000
	v_mov_b32_e32 v156, 0x7fc00000
	v_mov_b32_e32 v157, 0x7fc00000
	v_mov_b32_e32 v158, 0x7fc00000
	v_mov_b32_e32 v159, 0x7fc00000
	v_mov_b32_e32 v204, 0
	v_mov_b32_e32 v205, 0
	v_mov_b32_e32 v206, 0
	v_mov_b32_e32 v207, 0
	s_waitcnt lgkmcnt(0)
	v_readfirstlane_b32 s101, v92
	v_readfirstlane_b32 s100, v93
	v_mov_b32_e32 v72, 0
	v_mov_b32_e32 v73, 0
	v_mov_b32_e32 v74, 0
	v_mov_b32_e32 v75, 0
	v_mov_b32_e32 v76, 0
	v_mov_b32_e32 v77, 0
	v_mov_b32_e32 v78, 0
	v_mov_b32_e32 v79, 0
	v_mov_b32_e32 v80, 0
	v_mov_b32_e32 v81, 0
	v_mov_b32_e32 v82, 0
	v_mov_b32_e32 v83, 0
	v_mov_b32_e32 v84, 0
	v_mov_b32_e32 v85, 0
	v_mov_b32_e32 v86, 0
	v_mov_b32_e32 v87, 0
	v_mov_b32_e32 v88, 0
	v_mov_b32_e32 v89, 0
	v_mov_b32_e32 v90, 0
	v_mov_b32_e32 v91, 0
	v_mov_b32_e32 v92, 0
	v_mov_b32_e32 v93, 0
	v_mov_b32_e32 v94, 0
	v_mov_b32_e32 v95, 0
	s_add_i32 s12, s19, -1
	s_and_b32 s18, s12, 3
	s_mulk_i32 s18, 0x4800
	s_cmp_lg_u32 s49, 0
	s_cselect_b32 s12, s18, 0
	v_add_u32_e32 v200, s12, v251
	ds_read_b128 v[128:131], v200 offset:16384
	ds_read_b128 v[132:135], v200 offset:20992
	ds_read_b128 v[136:139], v200 offset:25600
	s_cbranch_execnz .LBB0_435
	s_branch .LBB0_434

; #define FLAS __attribute__((address_space(3)))
; __device__ __forceinline__ void attn_unit_a(FLAS unsigned char* lds, const Unit u) {
;     ...
;         if (i + 2 < NT) { kreg = *(const u32x4*)(ksrc + (size_t)(u.t_lo + i + 2) * 64 * u.ldk);
; #pragma unroll
;             for (int j = 0; j < 2; ++j) vreg[j] = *(const u32x4*)(vsrc + (size_t)j * 64 * MTOK + (u.t_lo + i + 2) * 64); }
;         const int vsp = (i == 0) ? 0 : ((i - 1) & 3);
;         const FLAS unsigned char* vb_ = lds + LA_V + vsp * VBUF + r32 * VPITCH + hi * 16;
;         const FLAS unsigned char* kb = lds + LA_K + ((i + 1) & 1) * KBUF;
;     ...
;         u32x4 vr[3];
; #pragma unroll
;         for (int m = 0; m < 3; ++m) vr[m] = FA_VFRAG(m);
;         const float off = cbC - mrun;
;         FA_SB();
;         float ra, rb, rm;
;         FA_PVM(0); pC0[0] = fadd_s(pC0[0], off); pC1[0] = fadd_s(pC1[0], off); pC0[1] = fadd_s(pC0[1], off); pC1[1] = fadd_s(pC1[1], off); pC0[2] = fadd_s(pC0[2], off); pC1[2] = fadd_s(pC1[2], off); FA_SB();
;         FA_PVM(1); ra = __builtin_fmaxf(__builtin_fmaxf(pC0[0], pC0[1]), pC0[2]); rb = __builtin_fmaxf(__builtin_fmaxf(pC1[0], pC1[1]), pC1[2]); pC0[3] = fadd_s(pC0[3], off); pC1[3] = fadd_s(pC1[3], off); pC0[4] = fadd_s(pC0[4], off); pC1[4] = fadd_s(pC1[4], off); FA_SB();
;         FA_PVM(2); ra = __builtin_fmaxf(__builtin_fmaxf(ra, pC0[3]), pC0[4]); rb = __builtin_fmaxf(__builtin_fmaxf(rb, pC1[3]), pC1[4]); pC0[5] = fadd_s(pC0[5], off); pC1[5] = fadd_s(pC1[5], off); pC0[6] = fadd_s(pC0[6], off); pC1[6] = fadd_s(pC1[6], off); FA_SB();
;         FA_PVM(3); ra = __builtin_fmaxf(__builtin_fmaxf(ra, pC0[5]), pC0[6]); rb = __builtin_fmaxf(__builtin_fmaxf(rb, pC1[5]), pC1[6]); pC0[7] = fadd_s(pC0[7], off); pC1[7] = fadd_s(pC1[7], off); pC0[8] = fadd_s(pC0[8], off); pC1[8] = fadd_s(pC1[8], off); FA_SB();
;         FA_PVM(4); ra = __builtin_fmaxf(__builtin_fmaxf(ra, pC0[7]), pC0[8]); rb = __builtin_fmaxf(__builtin_fmaxf(rb, pC1[7]), pC1[8]); pC0[9] = fadd_s(pC0[9], off); pC1[9] = fadd_s(pC1[9], off); pC0[10] = fadd_s(pC0[10], off); pC1[10] = fadd_s(pC1[10], off); FA_SB();
;         FA_PVM(5); ra = __builtin_fmaxf(__builtin_fmaxf(ra, pC0[9]), pC0[10]); rb = __builtin_fmaxf(__builtin_fmaxf(rb, pC1[9]), pC1[10]); pC0[11] = fadd_s(pC0[11], off); pC1[11] = fadd_s(pC1[11], off); pC0[12] = fadd_s(pC0[12], off); pC1[12] = fadd_s(pC1[12], off); FA_SB();
.LBB0_435:
	s_cmpk_lt_u32 s19, 0x7e
	s_cselect_b64 s[0:1], -1, 0
	s_cmpk_gt_u32 s19, 0x7d
	s_cselect_b64 s[4:5], -1, 0
	s_xor_b64 s[20:21], s[24:25], -1
	s_waitcnt lgkmcnt(2)
	v_mfma_f32_32x32x16_bf16 v[48:63], v[128:131], v[204:207], v[48:63]
	ds_read_b128 v[128:131], v200 offset:30208
	s_and_b64 vcc, exec, s[4:5]
	v_lshl_add_u64 v[234:235], v[230:231], 0, v[208:209]
	v_lshl_add_u64 v[232:233], v[228:229], 0, v[208:209]
	s_cbranch_vccnz .LBB0_437
	v_add_co_u32_e32 v142, vcc, 0xd660000, v234
	s_nop 1
	v_addc_co_u32_e32 v143, vcc, 0, v235, vcc
	global_load_dwordx4 v[176:179], v[142:143], off
	v_add_co_u32_e32 v142, vcc, 0x13600000, v232
	s_nop 1
	v_addc_co_u32_e32 v143, vcc, 0, v233, vcc
	global_load_dwordx4 v[180:183], v[142:143], off offset:256
	v_add_co_u32_e32 v142, vcc, 0x13a00000, v232
	s_nop 1
	v_addc_co_u32_e32 v143, vcc, 0, v233, vcc
	global_load_dwordx4 v[184:187], v[142:143], off offset:256
.LBB0_437:
	v_max3_f32 v140, v96, v97, v98
	v_max3_f32 v141, v112, v113, v114
	v_cvt_pk_bf16_f32 v196, v72, v73
	v_cvt_pk_bf16_f32 v197, v74, v75
	v_add_f32_e32 v212, v80, v212
	v_add_f32_e32 v212, v81, v212
	s_waitcnt lgkmcnt(2)
	v_mfma_f32_32x32x16_bf16 v[32:47], v[132:135], v[204:207], v[32:47]
	ds_read_b128 v[132:135], v200 offset:16416
	v_max3_f32 v140, v140, v99, v100
	v_max3_f32 v141, v141, v115, v116
	v_cvt_pk_bf16_f32 v198, v76, v77
	v_cvt_pk_bf16_f32 v199, v78, v79
	v_add_f32_e32 v212, v82, v212
	v_add_f32_e32 v212, v83, v212
	s_waitcnt lgkmcnt(2)
	v_mfma_f32_32x32x16_bf16 v[16:31], v[136:139], v[204:207], v[16:31]
	ds_read_b128 v[136:139], v200 offset:21024
	v_max3_f32 v140, v140, v101, v102
	v_max3_f32 v141, v141, v117, v118
	v_cvt_pk_bf16_f32 v192, v80, v81
	v_cvt_pk_bf16_f32 v193, v82, v83
	v_add_f32_e32 v212, v84, v212
	v_add_f32_e32 v212, v85, v212
	s_waitcnt lgkmcnt(2)
	v_mfma_f32_32x32x16_bf16 v[0:15], v[128:131], v[204:207], v[0:15]
	ds_read_b128 v[128:131], v200 offset:25632
	v_max3_f32 v140, v140, v103, v104
	v_max3_f32 v141, v141, v119, v120
	v_cvt_pk_bf16_f32 v194, v84, v85
	v_cvt_pk_bf16_f32 v195, v86, v87
	v_add_f32_e32 v212, v86, v212
	v_add_f32_e32 v212, v87, v212
	s_waitcnt lgkmcnt(2)
	v_mfma_f32_32x32x16_bf16 v[48:63], v[132:135], v[196:199], v[48:63]
	ds_read_b128 v[132:135], v200 offset:30240
	v_max3_f32 v140, v140, v105, v106
	v_max3_f32 v141, v141, v121, v122
	v_cvt_pk_bf16_f32 v188, v88, v89
	v_cvt_pk_bf16_f32 v189, v90, v91
	v_add_f32_e32 v212, v88, v212
	v_add_f32_e32 v212, v89, v212
	s_waitcnt lgkmcnt(2)
	v_mfma_f32_32x32x16_bf16 v[32:47], v[136:139], v[196:199], v[32:47]
	ds_read_b128 v[136:139], v200 offset:16448
	v_max3_f32 v140, v140, v107, v108
	v_max3_f32 v141, v141, v123, v124
	v_cvt_pk_bf16_f32 v190, v92, v93
	v_cvt_pk_bf16_f32 v191, v94, v95
	v_add_f32_e32 v212, v90, v212
	v_add_f32_e32 v212, v91, v212
	s_waitcnt lgkmcnt(2)
	v_mfma_f32_32x32x16_bf16 v[16:31], v[128:131], v[196:199], v[16:31]
	ds_read_b128 v[128:131], v200 offset:21056
	v_max3_f32 v140, v140, v109, v110
	v_max3_f32 v141, v141, v125, v126
	v_add_f32_e32 v212, v92, v212
	v_add_f32_e32 v212, v93, v212
	s_waitcnt lgkmcnt(2)
	v_mfma_f32_32x32x16_bf16 v[0:15], v[132:135], v[196:199], v[0:15]
	ds_read_b128 v[132:135], v200 offset:25664
	v_max3_f32 v140, v140, v141, v111
	v_max_f32_e32 v140, v140, v127
	v_add_f32_e32 v212, v94, v212
	v_add_f32_e32 v212, v95, v212
	v_mov_b32_e32 v141, v140
	s_nop 1
	v_permlane32_swap_b32 v140, v141
	s_nop 1
	s_nop 0
	v_max_f32_e32 v140, v140, v141
	s_andn2_b64 vcc, exec, s[20:21]
	s_cbranch_vccnz .LBB0_440
	v_cmp_lt_f32_e32 vcc, s39, v140
	s_cbranch_vccnz .Lresc_e
	s_mov_b64 s[20:21], 0

; #define FLAS __attribute__((address_space(3)))
; #define FA_SB() __builtin_amdgcn_sched_barrier(0)
; #define FA_EXP2(J, PX, R) do { const float e0_ = __builtin_amdgcn_exp2f(PX[R]), e1_ = __builtin_amdgcn_exp2f(PX[(R) + 1]); ps += e0_; ps += e1_; PWN[(J) >> 2][(J) & 3] = cvtpk(e0_, e1_); } while (0)
; __device__ __forceinline__ void attn_unit_a(FLAS unsigned char* lds, const Unit u) {
;     ...
;         kf[0] = FA_KF(2, 0); kf[1] = FA_KF(2, 1); FA_EXP2(9, pC1, 2); FA_SB();
;         pN0 = __builtin_amdgcn_mfma_f32_32x32x16_bf16(kf[2], qr[1], pN0, 0, 0, 0); FA_EXP2(10, pC1, 4); FA_SB();
;         pN1 = __builtin_amdgcn_mfma_f32_32x32x16_bf16(kf[3], qr[1], pN1, 0, 0, 0); kf[2] = FA_KF(3, 0); kf[3] = FA_KF(3, 1); FA_EXP2(11, pC1, 6); FA_SB();
;         pN0 = __builtin_amdgcn_mfma_f32_32x32x16_bf16(kf[0], qr[2], pN0, 0, 0, 0); FA_EXP2(12, pC1, 8); FA_SB();
;         pN1 = __builtin_amdgcn_mfma_f32_32x32x16_bf16(kf[1], qr[2], pN1, 0, 0, 0); FA_EXP2(13, pC1, 10); FA_SB();
;         pN0 = __builtin_amdgcn_mfma_f32_32x32x16_bf16(kf[2], qr[3], pN0, 0, 0, 0); FA_EXP2(14, pC1, 12); FA_SB();
;         pN1 = __builtin_amdgcn_mfma_f32_32x32x16_bf16(kf[3], qr[3], pN1, 0, 0, 0); FA_EXP2(15, pC1, 14); FA_SB();
;     ...
;         lsum += ps; cbC = cbN;
;         if (i + 2 < NT) { *(FLAS u32x4*)(lds + LA_K + (i & 1) * KBUF + kdst) = kreg;
; #pragma unroll
;             for (int j = 0; j < 2; ++j) { *(FLAS u32x2*)(lds + LA_V + ((i + 2) & 3) * VBUF + vdst + j * 64 * VPITCH) = (u32x2){vreg[j].x, vreg[j].y}; *(FLAS u32x2*)(lds + LA_V + ((i + 2) & 3) * VBUF + vdst + j * 64 * VPITCH + 16) = (u32x2){vreg[j].z, vreg[j].w}; } }
.Lk2_e:
	ds_read_b128 v[128:131], v249 offset:8192
	ds_read_b128 v[132:135], v249 offset:8704
	s_add_i32 s34, s19, 2
	v_mfma_f32_32x32x16_bf16 v[64:79], v[196:199], v[164:167], v[64:79]
	v_exp_f32_e32 v116, v116
	v_exp_f32_e32 v117, v117
	v_mfma_f32_32x32x16_bf16 v[80:95], v[192:195], v[164:167], v[80:95]
	ds_read_b128 v[136:139], v250 offset:8192
	ds_read_b128 v[140:143], v250 offset:8704
	s_and_b32 s0, s34, 2
	s_mulk_i32 s0, 0x4800
	v_add_u32_e32 v188, s0, v245
	v_add_u32_e32 v189, 0x4000, v188
	v_add_u32_e32 v188, 0x6000, v188
	s_waitcnt vmcnt(2)
	ds_write_b128 v225, v[176:179]
	s_waitcnt vmcnt(1)
	ds_write2_b64 v189, v[180:181], v[182:183] offset1:2
	s_waitcnt vmcnt(0)
	ds_write2_b64 v188, v[184:185], v[186:187] offset0:128 offset1:130
	v_exp_f32_e32 v118, v118
	v_exp_f32_e32 v119, v119
	s_and_b32 s0, s19, 2
	s_mulk_i32 s0, 0x4800
	v_add_u32_e32 v201, s0, v251
	s_waitcnt lgkmcnt(6)
	v_mfma_f32_32x32x16_bf16 v[64:79], v[128:131], v[168:171], v[64:79]
	ds_read_b128 v[128:131], v201 offset:16384
	v_exp_f32_e32 v120, v120
	v_exp_f32_e32 v121, v121
	s_waitcnt lgkmcnt(6)
	v_mfma_f32_32x32x16_bf16 v[80:95], v[132:135], v[168:171], v[80:95]
	ds_read_b128 v[132:135], v201 offset:20992
	v_exp_f32_e32 v122, v122
	v_exp_f32_e32 v123, v123
	s_waitcnt lgkmcnt(6)
	v_mfma_f32_32x32x16_bf16 v[64:79], v[136:139], v[172:175], v[64:79]
	ds_read_b128 v[136:139], v201 offset:25600
	v_exp_f32_e32 v124, v124
	v_exp_f32_e32 v125, v125
	s_waitcnt lgkmcnt(6)
	v_mfma_f32_32x32x16_bf16 v[80:95], v[140:143], v[172:175], v[80:95]
	v_exp_f32_e32 v126, v126
	v_exp_f32_e32 v127, v127
	v_cvt_pk_bf16_f32 v140, v96, v97
	v_cvt_pk_bf16_f32 v141, v98, v99
	v_cvt_pk_bf16_f32 v142, v100, v101
	v_cvt_pk_bf16_f32 v143, v102, v103

; #define FLAS __attribute__((address_space(3)))
; __device__ __forceinline__ void attn_unit_a(FLAS unsigned char* lds, const Unit u) {
;     ...
;         if (i + 2 < NT) { kreg = *(const u32x4*)(ksrc + (size_t)(u.t_lo + i + 2) * 64 * u.ldk);
; #pragma unroll
;             for (int j = 0; j < 2; ++j) vreg[j] = *(const u32x4*)(vsrc + (size_t)j * 64 * MTOK + (u.t_lo + i + 2) * 64); }
;         const int vsp = (i == 0) ? 0 : ((i - 1) & 3);
;         const FLAS unsigned char* vb_ = lds + LA_V + vsp * VBUF + r32 * VPITCH + hi * 16;
;         const FLAS unsigned char* kb = lds + LA_K + ((i + 1) & 1) * KBUF;
;     ...
;         u32x4 vr[3];
; #pragma unroll
;         for (int m = 0; m < 3; ++m) vr[m] = FA_VFRAG(m);
;         const float off = cbC - mrun;
;         FA_SB();
;         float ra, rb, rm;
;         FA_PVM(0); pC0[0] = fadd_s(pC0[0], off); pC1[0] = fadd_s(pC1[0], off); pC0[1] = fadd_s(pC0[1], off); pC1[1] = fadd_s(pC1[1], off); pC0[2] = fadd_s(pC0[2], off); pC1[2] = fadd_s(pC1[2], off); FA_SB();
;         FA_PVM(1); ra = __builtin_fmaxf(__builtin_fmaxf(pC0[0], pC0[1]), pC0[2]); rb = __builtin_fmaxf(__builtin_fmaxf(pC1[0], pC1[1]), pC1[2]); pC0[3] = fadd_s(pC0[3], off); pC1[3] = fadd_s(pC1[3], off); pC0[4] = fadd_s(pC0[4], off); pC1[4] = fadd_s(pC1[4], off); FA_SB();
;         FA_PVM(2); ra = __builtin_fmaxf(__builtin_fmaxf(ra, pC0[3]), pC0[4]); rb = __builtin_fmaxf(__builtin_fmaxf(rb, pC1[3]), pC1[4]); pC0[5] = fadd_s(pC0[5], off); pC1[5] = fadd_s(pC1[5], off); pC0[6] = fadd_s(pC0[6], off); pC1[6] = fadd_s(pC1[6], off); FA_SB();
;         FA_PVM(3); ra = __builtin_fmaxf(__builtin_fmaxf(ra, pC0[5]), pC0[6]); rb = __builtin_fmaxf(__builtin_fmaxf(rb, pC1[5]), pC1[6]); pC0[7] = fadd_s(pC0[7], off); pC1[7] = fadd_s(pC1[7], off); pC0[8] = fadd_s(pC0[8], off); pC1[8] = fadd_s(pC1[8], off); FA_SB();
;         FA_PVM(4); ra = __builtin_fmaxf(__builtin_fmaxf(ra, pC0[7]), pC0[8]); rb = __builtin_fmaxf(__builtin_fmaxf(rb, pC1[7]), pC1[8]); pC0[9] = fadd_s(pC0[9], off); pC1[9] = fadd_s(pC1[9], off); pC0[10] = fadd_s(pC0[10], off); pC1[10] = fadd_s(pC1[10], off); FA_SB();
;         FA_PVM(5); ra = __builtin_fmaxf(__builtin_fmaxf(ra, pC0[9]), pC0[10]); rb = __builtin_fmaxf(__builtin_fmaxf(rb, pC1[9]), pC1[10]); pC0[11] = fadd_s(pC0[11], off); pC1[11] = fadd_s(pC1[11], off); pC0[12] = fadd_s(pC0[12], off); pC1[12] = fadd_s(pC1[12], off); FA_SB();
.LBB0_458:
	s_cmpk_lt_u32 s19, 0x7d
	s_cselect_b64 s[20:21], -1, 0
	s_waitcnt lgkmcnt(2)
	v_mfma_f32_32x32x16_bf16 v[48:63], v[128:131], v[140:143], v[48:63]
	ds_read_b128 v[128:131], v201 offset:30208
	s_cmpk_gt_u32 s19, 0x7c
	s_cbranch_scc1 .LBB0_460
	v_add_co_u32_e32 v98, vcc, 0xd690000, v234
	s_nop 1
	v_addc_co_u32_e32 v99, vcc, 0, v235, vcc
	global_load_dwordx4 v[176:179], v[98:99], off
	v_add_co_u32_e32 v98, vcc, 0x13600000, v232
	s_nop 1
	v_addc_co_u32_e32 v99, vcc, 0, v233, vcc
	global_load_dwordx4 v[180:183], v[98:99], off offset:384
	v_add_co_u32_e32 v98, vcc, 0x13a00000, v232
	s_nop 1
	v_addc_co_u32_e32 v99, vcc, 0, v233, vcc
	global_load_dwordx4 v[184:187], v[98:99], off offset:384
.LBB0_460:
	v_max3_f32 v96, v64, v65, v66
	v_max3_f32 v97, v80, v81, v82
	v_cvt_pk_bf16_f32 v232, v104, v105
	v_cvt_pk_bf16_f32 v233, v106, v107
	v_add_f32_e32 v212, v112, v212
	v_add_f32_e32 v212, v113, v212
	s_waitcnt lgkmcnt(2)
	v_mfma_f32_32x32x16_bf16 v[32:47], v[132:135], v[140:143], v[32:47]
	ds_read_b128 v[132:135], v201 offset:16416
	v_max3_f32 v96, v96, v67, v68
	v_max3_f32 v97, v97, v83, v84
	v_cvt_pk_bf16_f32 v234, v108, v109
	v_cvt_pk_bf16_f32 v235, v110, v111
	v_add_f32_e32 v212, v114, v212
	v_add_f32_e32 v212, v115, v212
	s_waitcnt lgkmcnt(2)
	v_mfma_f32_32x32x16_bf16 v[16:31], v[136:139], v[140:143], v[16:31]
	ds_read_b128 v[136:139], v201 offset:21024
	v_max3_f32 v96, v96, v69, v70
	v_max3_f32 v97, v97, v85, v86
	v_add_f32_e32 v212, v116, v212
	v_add_f32_e32 v212, v117, v212
	s_waitcnt lgkmcnt(2)
	v_mfma_f32_32x32x16_bf16 v[0:15], v[128:131], v[140:143], v[0:15]
	ds_read_b128 v[128:131], v201 offset:25632
	v_max3_f32 v96, v96, v71, v72
	v_max3_f32 v97, v97, v87, v88
	v_add_f32_e32 v212, v118, v212
	v_add_f32_e32 v212, v119, v212
	s_waitcnt lgkmcnt(2)
	v_mfma_f32_32x32x16_bf16 v[48:63], v[132:135], v[232:235], v[48:63]
	ds_read_b128 v[132:135], v201 offset:30240
	v_max3_f32 v96, v96, v73, v74
	v_max3_f32 v97, v97, v89, v90
	v_cvt_pk_bf16_f32 v140, v112, v113
	v_cvt_pk_bf16_f32 v141, v114, v115
	v_add_f32_e32 v212, v120, v212
	v_add_f32_e32 v212, v121, v212
	s_waitcnt lgkmcnt(2)
	v_mfma_f32_32x32x16_bf16 v[32:47], v[136:139], v[232:235], v[32:47]
	ds_read_b128 v[136:139], v201 offset:16448
	v_max3_f32 v96, v96, v75, v76
	v_max3_f32 v97, v97, v91, v92
	v_cvt_pk_bf16_f32 v142, v116, v117
	v_cvt_pk_bf16_f32 v143, v118, v119
	v_add_f32_e32 v212, v122, v212
	v_add_f32_e32 v212, v123, v212
	s_waitcnt lgkmcnt(2)
	v_mfma_f32_32x32x16_bf16 v[16:31], v[128:131], v[232:235], v[16:31]
	ds_read_b128 v[128:131], v201 offset:21056
	v_max3_f32 v96, v96, v77, v78
	v_max3_f32 v97, v97, v93, v94
	v_add_f32_e32 v212, v124, v212
	v_add_f32_e32 v212, v125, v212
	s_waitcnt lgkmcnt(2)
	v_mfma_f32_32x32x16_bf16 v[0:15], v[132:135], v[232:235], v[0:15]
	ds_read_b128 v[132:135], v201 offset:25664
	v_max3_f32 v96, v96, v97, v79
	v_max_f32_e32 v96, v96, v95
	v_add_f32_e32 v212, v126, v212
	v_add_f32_e32 v212, v127, v212
	v_mov_b32_e32 v97, v96
	s_nop 1
	v_permlane32_swap_b32 v96, v97
	s_nop 1
	s_nop 0
	v_max_f32_e32 v96, v96, v97
	v_cmp_lt_f32_e32 vcc, s39, v96
	s_mov_b64 s[0:1], 0
	s_cbranch_vccnz .Lresc_o

; #define FLAS __attribute__((address_space(3)))
; #define FA_SB() __builtin_amdgcn_sched_barrier(0)
; #define FA_EXP2(J, PX, R) do { const float e0_ = __builtin_amdgcn_exp2f(PX[R]), e1_ = __builtin_amdgcn_exp2f(PX[(R) + 1]); ps += e0_; ps += e1_; PWN[(J) >> 2][(J) & 3] = cvtpk(e0_, e1_); } while (0)
; __device__ __forceinline__ void attn_unit_a(FLAS unsigned char* lds, const Unit u) {
;     ...
;         kf[0] = FA_KF(2, 0); kf[1] = FA_KF(2, 1); FA_EXP2(9, pC1, 2); FA_SB();
;         pN0 = __builtin_amdgcn_mfma_f32_32x32x16_bf16(kf[2], qr[1], pN0, 0, 0, 0); FA_EXP2(10, pC1, 4); FA_SB();
;         pN1 = __builtin_amdgcn_mfma_f32_32x32x16_bf16(kf[3], qr[1], pN1, 0, 0, 0); kf[2] = FA_KF(3, 0); kf[3] = FA_KF(3, 1); FA_EXP2(11, pC1, 6); FA_SB();
;         pN0 = __builtin_amdgcn_mfma_f32_32x32x16_bf16(kf[0], qr[2], pN0, 0, 0, 0); FA_EXP2(12, pC1, 8); FA_SB();
;         pN1 = __builtin_amdgcn_mfma_f32_32x32x16_bf16(kf[1], qr[2], pN1, 0, 0, 0); FA_EXP2(13, pC1, 10); FA_SB();
;         pN0 = __builtin_amdgcn_mfma_f32_32x32x16_bf16(kf[2], qr[3], pN0, 0, 0, 0); FA_EXP2(14, pC1, 12); FA_SB();
;         pN1 = __builtin_amdgcn_mfma_f32_32x32x16_bf16(kf[3], qr[3], pN1, 0, 0, 0); FA_EXP2(15, pC1, 14); FA_SB();
;     ...
;         lsum += ps; cbC = cbN;
;         if (i + 2 < NT) { *(FLAS u32x4*)(lds + LA_K + (i & 1) * KBUF + kdst) = kreg;
; #pragma unroll
;             for (int j = 0; j < 2; ++j) { *(FLAS u32x2*)(lds + LA_V + ((i + 2) & 3) * VBUF + vdst + j * 64 * VPITCH) = (u32x2){vreg[j].x, vreg[j].y}; *(FLAS u32x2*)(lds + LA_V + ((i + 2) & 3) * VBUF + vdst + j * 64 * VPITCH + 16) = (u32x2){vreg[j].z, vreg[j].w}; } }
.Lk2_o:
	ds_read_b128 v[128:131], v249
	ds_read_b128 v[132:135], v249 offset:512
	v_mfma_f32_32x32x16_bf16 v[96:111], v[192:195], v[164:167], v[96:111]
	v_exp_f32_e32 v84, v84
	v_exp_f32_e32 v85, v85
	v_mfma_f32_32x32x16_bf16 v[112:127], v[188:191], v[164:167], v[112:127]
	ds_read_b128 v[136:139], v250
	ds_read_b128 v[140:143], v250 offset:512
	v_add_u32_e32 v204, s18, v245
	v_add_u32_e32 v205, 0x4000, v204
	v_add_u32_e32 v204, 0x6000, v204
	s_waitcnt vmcnt(2)
	ds_write_b128 v225, v[176:179] offset:8192
	s_waitcnt vmcnt(1)
	ds_write2_b64 v205, v[180:181], v[182:183] offset1:2
	s_waitcnt vmcnt(0)
	ds_write2_b64 v204, v[184:185], v[186:187] offset0:128 offset1:130
	v_exp_f32_e32 v86, v86
	v_exp_f32_e32 v87, v87
	s_add_i32 s12, s34, -1
	s_and_b32 s18, s12, 3
	s_mulk_i32 s18, 0x4800
	v_add_u32_e32 v200, s18, v251
	s_waitcnt lgkmcnt(6)
	v_mfma_f32_32x32x16_bf16 v[96:111], v[128:131], v[168:171], v[96:111]
	ds_read_b128 v[128:131], v200 offset:16384
	v_exp_f32_e32 v88, v88
	v_exp_f32_e32 v89, v89
	s_waitcnt lgkmcnt(6)
	v_mfma_f32_32x32x16_bf16 v[112:127], v[132:135], v[168:171], v[112:127]
	ds_read_b128 v[132:135], v200 offset:20992
	v_exp_f32_e32 v90, v90
	v_exp_f32_e32 v91, v91
	s_waitcnt lgkmcnt(6)
	v_mfma_f32_32x32x16_bf16 v[96:111], v[136:139], v[172:175], v[96:111]
	ds_read_b128 v[136:139], v200 offset:25600
	v_exp_f32_e32 v92, v92
	v_exp_f32_e32 v93, v93
	s_waitcnt lgkmcnt(6)
	v_mfma_f32_32x32x16_bf16 v[112:127], v[140:143], v[172:175], v[112:127]
	v_exp_f32_e32 v94, v94
	v_exp_f32_e32 v95, v95
